# weight transposes: the two workgroups that compute the compress bias take no transpose items (items re-strided over the other 254)
# speedup vs baseline: 1.0050x; 1.0050x over previous
.LBB0_27:
	s_add_i32 s12, s18, s81
	s_cmp_lt_u32 s12, 16
	s_cbranch_scc1 .LBB0_68
	s_mov_b64 s[4:5], 0xb00000
	s_waitcnt vmcnt(0) lgkmcnt(0)
	v_lshl_add_u64 v[6:7], v[4:5], 0, s[4:5]
	s_mov_b64 s[4:5], 0x1300000
	v_lshl_add_u64 v[8:9], v[4:5], 0, s[4:5]
	s_mov_b64 s[4:5], 0x1b00000
	v_lshl_add_u64 v[10:11], v[4:5], 0, s[4:5]
	s_mov_b64 s[4:5], 0x1d00000
	v_lshl_add_u64 v[12:13], v[4:5], 0, s[4:5]
	s_mov_b64 s[4:5], 0x2000000
	v_lshl_add_u64 v[14:15], v[4:5], 0, s[4:5]
	s_mov_b64 s[4:5], 0x2080000
	v_lshl_add_u64 v[16:17], v[4:5], 0, s[4:5]
	s_mov_b64 s[4:5], 0x2180000
	v_lshl_add_u64 v[18:19], v[4:5], 0, s[4:5]
	v_readlane_b32 s4, v255, 10
	v_readlane_b32 s5, v255, 11
	s_mov_b32 s16, s4
	s_mul_i32 s4, s4, 0x566000
	s_mov_b32 s5, s75
	s_lshl_b32 s13, s16, 1
	s_lshl_b32 s6, s16, 18
	s_mov_b32 s7, s75
	s_lshl_b32 s8, s16, 19
	s_mov_b32 s9, s75
	s_lshl_b32 s10, s16, 20
	s_mov_b32 s11, s75
	s_lshl_b32 s16, s16, 22
	s_mov_b32 s17, s75
	s_and_b32 s28, s18, 1
	s_sub_i32 s29, s12, 16
	s_branch .LBB0_31

.LBB0_30:
	s_or_b64 exec, exec, s[22:23]
	s_lshl_b32 s26, s30, 6
	s_ashr_i32 s27, s26, 31
	s_mul_i32 s22, s18, s27
	s_mul_hi_u32 s23, s18, s26
	s_add_i32 s22, s23, s22
	s_mul_i32 s23, s19, s26
	s_add_i32 s23, s22, s23
	s_mul_i32 s22, s18, s26
	v_lshl_add_u64 v[24:25], s[22:23], 2, v[24:25]
	v_max_i32_e32 v0, 0, v26
	v_lshl_add_u64 v[24:25], v[0:1], 2, v[24:25]
	v_ashrrev_i32_e32 v30, 31, v23
	v_mad_u64_u32 v[32:33], s[24:25], s20, v23, 0
	v_mul_lo_u32 v31, s21, v23
	v_mul_lo_u32 v30, s20, v30
	v_add3_u32 v33, v33, v30, v31
	v_lshl_add_u64 v[20:21], v[32:33], 1, v[20:21]
	v_lshl_add_u64 v[20:21], s[26:27], 1, v[20:21]
	s_lshl_b64 s[24:25], s[18:19], 2
	v_cmp_gt_i32_e32 vcc, 0, v26
	s_addk_i32 s29, 0x7f0
	global_load_dword v64, v[24:25], off
	v_lshl_add_u64 v[24:25], v[24:25], 0, s[24:25]
	global_load_dword v65, v[24:25], off
	v_lshl_add_u64 v[24:25], v[24:25], 0, s[24:25]
	global_load_dword v66, v[24:25], off
	v_lshl_add_u64 v[24:25], v[24:25], 0, s[24:25]
	global_load_dword v67, v[24:25], off
	v_lshl_add_u64 v[24:25], v[24:25], 0, s[24:25]
	global_load_dword v68, v[24:25], off
	v_lshl_add_u64 v[24:25], v[24:25], 0, s[24:25]
	global_load_dword v69, v[24:25], off
	v_lshl_add_u64 v[24:25], v[24:25], 0, s[24:25]
	global_load_dword v70, v[24:25], off
	v_lshl_add_u64 v[24:25], v[24:25], 0, s[24:25]
	global_load_dword v71, v[24:25], off
	v_lshl_add_u64 v[24:25], v[24:25], 0, s[24:25]
	global_load_dword v72, v[24:25], off
	v_lshl_add_u64 v[24:25], v[24:25], 0, s[24:25]
	global_load_dword v73, v[24:25], off
	v_lshl_add_u64 v[24:25], v[24:25], 0, s[24:25]
	global_load_dword v74, v[24:25], off
	v_lshl_add_u64 v[24:25], v[24:25], 0, s[24:25]
	global_load_dword v75, v[24:25], off
	v_lshl_add_u64 v[24:25], v[24:25], 0, s[24:25]
	global_load_dword v76, v[24:25], off
	v_lshl_add_u64 v[24:25], v[24:25], 0, s[24:25]
	global_load_dword v77, v[24:25], off
	v_lshl_add_u64 v[24:25], v[24:25], 0, s[24:25]
	global_load_dword v78, v[24:25], off
	v_lshl_add_u64 v[24:25], v[24:25], 0, s[24:25]
	global_load_dword v79, v[24:25], off
	v_lshl_add_u64 v[24:25], v[24:25], 0, s[24:25]
	global_load_dword v80, v[24:25], off
	v_lshl_add_u64 v[24:25], v[24:25], 0, s[24:25]
	global_load_dword v81, v[24:25], off
	v_lshl_add_u64 v[24:25], v[24:25], 0, s[24:25]
	global_load_dword v82, v[24:25], off
	v_lshl_add_u64 v[24:25], v[24:25], 0, s[24:25]
	global_load_dword v83, v[24:25], off
	v_lshl_add_u64 v[24:25], v[24:25], 0, s[24:25]
	global_load_dword v84, v[24:25], off
	v_lshl_add_u64 v[24:25], v[24:25], 0, s[24:25]
	global_load_dword v85, v[24:25], off
	v_lshl_add_u64 v[24:25], v[24:25], 0, s[24:25]
	global_load_dword v86, v[24:25], off
	v_lshl_add_u64 v[24:25], v[24:25], 0, s[24:25]
	global_load_dword v87, v[24:25], off
	v_lshl_add_u64 v[24:25], v[24:25], 0, s[24:25]
	global_load_dword v88, v[24:25], off
	v_lshl_add_u64 v[24:25], v[24:25], 0, s[24:25]
	global_load_dword v89, v[24:25], off
	v_lshl_add_u64 v[24:25], v[24:25], 0, s[24:25]
	global_load_dword v90, v[24:25], off
	v_lshl_add_u64 v[24:25], v[24:25], 0, s[24:25]
	global_load_dword v91, v[24:25], off
	v_lshl_add_u64 v[24:25], v[24:25], 0, s[24:25]
	global_load_dword v92, v[24:25], off
	v_lshl_add_u64 v[24:25], v[24:25], 0, s[24:25]
	global_load_dword v93, v[24:25], off
	v_lshl_add_u64 v[24:25], v[24:25], 0, s[24:25]
	global_load_dword v94, v[24:25], off
	v_lshl_add_u64 v[24:25], v[24:25], 0, s[24:25]
	global_load_dword v95, v[24:25], off
	v_lshl_add_u64 v[24:25], v[24:25], 0, s[24:25]
	global_load_dword v96, v[24:25], off
	v_lshl_add_u64 v[24:25], v[24:25], 0, s[24:25]
	global_load_dword v97, v[24:25], off
	v_lshl_add_u64 v[24:25], v[24:25], 0, s[24:25]
	global_load_dword v98, v[24:25], off
	v_lshl_add_u64 v[24:25], v[24:25], 0, s[24:25]
	global_load_dword v99, v[24:25], off
	v_lshl_add_u64 v[24:25], v[24:25], 0, s[24:25]
	global_load_dword v100, v[24:25], off
	v_lshl_add_u64 v[24:25], v[24:25], 0, s[24:25]
	global_load_dword v101, v[24:25], off
	v_lshl_add_u64 v[24:25], v[24:25], 0, s[24:25]
	global_load_dword v102, v[24:25], off
	v_lshl_add_u64 v[24:25], v[24:25], 0, s[24:25]
	global_load_dword v103, v[24:25], off
	v_lshl_add_u64 v[24:25], v[24:25], 0, s[24:25]
	global_load_dword v104, v[24:25], off
	v_lshl_add_u64 v[24:25], v[24:25], 0, s[24:25]
	global_load_dword v105, v[24:25], off
	v_lshl_add_u64 v[24:25], v[24:25], 0, s[24:25]
	global_load_dword v106, v[24:25], off
	v_lshl_add_u64 v[24:25], v[24:25], 0, s[24:25]
	global_load_dword v107, v[24:25], off
	v_lshl_add_u64 v[24:25], v[24:25], 0, s[24:25]
	global_load_dword v108, v[24:25], off
	v_lshl_add_u64 v[24:25], v[24:25], 0, s[24:25]
	global_load_dword v109, v[24:25], off
	v_lshl_add_u64 v[24:25], v[24:25], 0, s[24:25]
	global_load_dword v110, v[24:25], off
	v_lshl_add_u64 v[24:25], v[24:25], 0, s[24:25]
	global_load_dword v111, v[24:25], off
	v_lshl_add_u64 v[24:25], v[24:25], 0, s[24:25]
	global_load_dword v112, v[24:25], off
	v_lshl_add_u64 v[24:25], v[24:25], 0, s[24:25]
	global_load_dword v113, v[24:25], off
	v_lshl_add_u64 v[24:25], v[24:25], 0, s[24:25]
	global_load_dword v114, v[24:25], off
	v_lshl_add_u64 v[24:25], v[24:25], 0, s[24:25]
	global_load_dword v115, v[24:25], off
	v_lshl_add_u64 v[24:25], v[24:25], 0, s[24:25]
	global_load_dword v116, v[24:25], off
	v_lshl_add_u64 v[24:25], v[24:25], 0, s[24:25]
	global_load_dword v117, v[24:25], off
	v_lshl_add_u64 v[24:25], v[24:25], 0, s[24:25]
	global_load_dword v118, v[24:25], off
	v_lshl_add_u64 v[24:25], v[24:25], 0, s[24:25]
	global_load_dword v119, v[24:25], off
	v_lshl_add_u64 v[24:25], v[24:25], 0, s[24:25]
	global_load_dword v120, v[24:25], off
	v_lshl_add_u64 v[24:25], v[24:25], 0, s[24:25]
	global_load_dword v121, v[24:25], off
	v_lshl_add_u64 v[24:25], v[24:25], 0, s[24:25]
	global_load_dword v122, v[24:25], off
	v_lshl_add_u64 v[24:25], v[24:25], 0, s[24:25]
	global_load_dword v123, v[24:25], off
	v_lshl_add_u64 v[24:25], v[24:25], 0, s[24:25]
	global_load_dword v124, v[24:25], off
	v_lshl_add_u64 v[24:25], v[24:25], 0, s[24:25]
	global_load_dword v125, v[24:25], off
	v_lshl_add_u64 v[24:25], v[24:25], 0, s[24:25]
	global_load_dword v126, v[24:25], off
	v_lshl_add_u64 v[24:25], v[24:25], 0, s[24:25]
	global_load_dword v127, v[24:25], off
	s_waitcnt vmcnt(56)
	v_cvt_pk_bf16_f32 v64, v64, v65
	v_cvt_pk_bf16_f32 v65, v66, v67
	v_cvt_pk_bf16_f32 v66, v68, v69
	v_cvt_pk_bf16_f32 v67, v70, v71
	v_cndmask_b32_e64 v64, v64, 0, vcc
	v_cndmask_b32_e64 v65, v65, 0, vcc
	v_cndmask_b32_e64 v66, v66, 0, vcc
	v_cndmask_b32_e64 v67, v67, 0, vcc
	global_store_dwordx4 v[20:21], v[64:67], off
	s_waitcnt vmcnt(49)
	v_cvt_pk_bf16_f32 v72, v72, v73
	v_cvt_pk_bf16_f32 v73, v74, v75
	v_cvt_pk_bf16_f32 v74, v76, v77
	v_cvt_pk_bf16_f32 v75, v78, v79
	v_cndmask_b32_e64 v72, v72, 0, vcc
	v_cndmask_b32_e64 v73, v73, 0, vcc
	v_cndmask_b32_e64 v74, v74, 0, vcc
	v_cndmask_b32_e64 v75, v75, 0, vcc
	global_store_dwordx4 v[20:21], v[72:75], off offset:16
	s_waitcnt vmcnt(42)
	v_cvt_pk_bf16_f32 v80, v80, v81
	v_cvt_pk_bf16_f32 v81, v82, v83
	v_cvt_pk_bf16_f32 v82, v84, v85
	v_cvt_pk_bf16_f32 v83, v86, v87
	v_cndmask_b32_e64 v80, v80, 0, vcc
	v_cndmask_b32_e64 v81, v81, 0, vcc
	v_cndmask_b32_e64 v82, v82, 0, vcc
	v_cndmask_b32_e64 v83, v83, 0, vcc
	global_store_dwordx4 v[20:21], v[80:83], off offset:32
	s_waitcnt vmcnt(35)
	v_cvt_pk_bf16_f32 v88, v88, v89
	v_cvt_pk_bf16_f32 v89, v90, v91
	v_cvt_pk_bf16_f32 v90, v92, v93
	v_cvt_pk_bf16_f32 v91, v94, v95
	v_cndmask_b32_e64 v88, v88, 0, vcc
	v_cndmask_b32_e64 v89, v89, 0, vcc
	v_cndmask_b32_e64 v90, v90, 0, vcc
	v_cndmask_b32_e64 v91, v91, 0, vcc
	global_store_dwordx4 v[20:21], v[88:91], off offset:48
	s_waitcnt vmcnt(28)
	v_cvt_pk_bf16_f32 v96, v96, v97
	v_cvt_pk_bf16_f32 v97, v98, v99
	v_cvt_pk_bf16_f32 v98, v100, v101
	v_cvt_pk_bf16_f32 v99, v102, v103
	v_cndmask_b32_e64 v96, v96, 0, vcc
	v_cndmask_b32_e64 v97, v97, 0, vcc
	v_cndmask_b32_e64 v98, v98, 0, vcc
	v_cndmask_b32_e64 v99, v99, 0, vcc
	global_store_dwordx4 v[20:21], v[96:99], off offset:64
	s_waitcnt vmcnt(21)
	v_cvt_pk_bf16_f32 v104, v104, v105
	v_cvt_pk_bf16_f32 v105, v106, v107
	v_cvt_pk_bf16_f32 v106, v108, v109
	v_cvt_pk_bf16_f32 v107, v110, v111
	v_cndmask_b32_e64 v104, v104, 0, vcc
	v_cndmask_b32_e64 v105, v105, 0, vcc
	v_cndmask_b32_e64 v106, v106, 0, vcc
	v_cndmask_b32_e64 v107, v107, 0, vcc
	global_store_dwordx4 v[20:21], v[104:107], off offset:80
	s_waitcnt vmcnt(14)
	v_cvt_pk_bf16_f32 v112, v112, v113
	v_cvt_pk_bf16_f32 v113, v114, v115
	v_cvt_pk_bf16_f32 v114, v116, v117
	v_cvt_pk_bf16_f32 v115, v118, v119
	v_cndmask_b32_e64 v112, v112, 0, vcc
	v_cndmask_b32_e64 v113, v113, 0, vcc
	v_cndmask_b32_e64 v114, v114, 0, vcc
	v_cndmask_b32_e64 v115, v115, 0, vcc
	global_store_dwordx4 v[20:21], v[112:115], off offset:96
	s_waitcnt vmcnt(7)
	v_cvt_pk_bf16_f32 v120, v120, v121
	v_cvt_pk_bf16_f32 v121, v122, v123
	v_cvt_pk_bf16_f32 v122, v124, v125
	v_cvt_pk_bf16_f32 v123, v126, v127
	v_cndmask_b32_e64 v120, v120, 0, vcc
	v_cndmask_b32_e64 v121, v121, 0, vcc
	v_cndmask_b32_e64 v122, v122, 0, vcc
	v_cndmask_b32_e64 v123, v123, 0, vcc
	global_store_dwordx4 v[20:21], v[120:123], off offset:112
	s_cmpk_gt_i32 s29, 0x10c3
	s_cbranch_scc1 .LBB0_68
